# A-attn non-uniform-bucket tiles: bias reads issued under the second half of the QK MFMAs, bias added with packed adds (op_sel swap) - these tiles set the pace of 37% of the iterations
# speedup vs baseline: 1.0022x; 1.0022x over previous
; template <int DQK, int VAR> ...
;     ...
;         __builtin_amdgcn_sched_barrier(0);
;         __builtin_amdgcn_s_setprio(1);
; #pragma unroll
;         for (int c = 0; c < 2; ++c) {
;             s[0][ch * 2 + c] = (f32x4){sinit, sinit, sinit, sinit}; s[1][ch * 2 + c] = s[0][ch * 2 + c];
; #pragma unroll
;             for (int ks = 0; ks < DQK / 32; ++ks) {
;                 s[0][ch * 2 + c] = __builtin_amdgcn_mfma_f32_16x16x32_bf16(kfr[c][ks], qf[0][ks], s[0][ch * 2 + c], 0, 0, 0);
; template <int DQK, int MODE>
; __device__ __forceinline__ void attn_unit(LAS unsigned char* lds, const AttnArgs& a, const unsigned char* lut) {
;     ...
;     for (int kt = kt_lo; kt <= kt_hi; ++kt) {
;         const int cur = (kt - kt_lo) & 1;
;         if (kt < kt_hi) ATT_STORE(cur ^ 1);
;         if (kt + 1 < kt_hi) ATT_LOAD(kt + 2);
;         const unsigned long long mwc0 = mwn0, mwc1 = mwn1;
;         if (MODE == 2 && kt < kt_hi) { mwn0 = a.mask[(long)qi * 128 + kt + 1]; mwn1 = a.mask[(long)(qi + 16) * 128 + kt + 1]; }
;         const LAS bf16_t* sK = (const LAS bf16_t*)(lds + cur * 24576); const LAS bf16_t* sVt = (const LAS bf16_t*)(lds + cur * 24576 + 14336);
;         const int key0 = kt * 64;
;         bool skip = key0 > wq_max;
;         if (MODE == 1) skip = skip || (key0 + 63 < wq_min - a.maxdist);
;         if (!skip) {
;             unsigned mlo[2] = {0u, 0u}, mhi[2] = {0u, 0u};
;             if (MODE == 0) {
;                 if (key0 + 63 <= wq_min) attn_tile<DQK, 0>(sK, sVt, sBias, qf, o, lsum, qi, key0, 0, mlo, mhi, nb, lr, lg);
;                 else attn_tile<DQK, 1>(sK, sVt, sBias, qf, o, lsum, qi, key0, 0, mlo, mhi, nb, lr, lg);
;             } else if (MODE == 1) {
;                 attn_tile<DQK, 2>(sK, sVt, sBias, qf, o, lsum, qi, key0, a.maxdist, mlo, mhi, nb, lr, lg);
;             } else {
;                 const unsigned long long w0 = mwc0 >> (lg * 4), w1 = mwc1 >> (lg * 4);
;                 mlo[0] = (unsigned)w0; mhi[0] = (unsigned)(w0 >> 32); mlo[1] = (unsigned)w1; mhi[1] = (unsigned)(w1 >> 32);
;                 const int uni = __builtin_amdgcn_readfirstlane((int)sUni[wid * 132 + kt]);
;                 if (uni) { const float ub = sBias[96 + wq_min - key0]; attn_tile<DQK, 3>(sK, sVt, sBias, qf, o, lsum, qi, key0, 0, mlo, mhi, nb + ub, lr, lg); }
;                 else attn_tile<DQK, 4>(sK, sVt, sBias, qf, o, lsum, qi, key0, 0, mlo, mhi, nb, lr, lg);
.LBB0_338:
	s_mulk_i32 s19, 0x6000
	v_lshrrev_b64 v[62:63], v60, v[62:63]
	v_lshrrev_b64 v[64:65], v54, v[64:65]
	s_add_i32 s0, s19, 0
	v_add3_u32 v96, s0, v0, v160
	s_movk_i32 s0, 0xf0
	v_lshlrev_b32_e32 v69, 4, v62
	v_lshrrev_b32_e32 v70, 12, v62
	v_lshlrev_b32_e32 v71, 4, v63
	v_lshrrev_b32_e32 v72, 12, v63
	v_lshlrev_b32_e32 v73, 4, v64
	v_lshrrev_b32_e32 v74, 12, v64
	v_lshlrev_b32_e32 v75, 4, v65
	v_lshrrev_b32_e32 v76, 12, v65
	v_and_or_b32 v69, v69, s0, v162
	v_and_or_b32 v70, v70, s0, v162
	v_and_or_b32 v71, v71, s0, v162
	v_and_or_b32 v72, v72, s0, v162
	v_and_or_b32 v73, v73, s0, v162
	v_and_or_b32 v74, v74, s0, v162
	v_and_or_b32 v75, v75, s0, v162
	v_and_or_b32 v76, v76, s0, v162
	s_mov_b32 vcc_lo, 0x76543210
	s_mov_b32 vcc_hi, 0xfedcba98
	v_readfirstlane_b32 s1, v97
	v_sub_f32_e32 v78, v217, v55
	s_nop 0
	s_cmp_lg_u32 s1, 0
	s_cselect_b64 s[36:37], -1, 0
	v_cndmask_b32_e64 v77, v56, v78, s[36:37]
	v_cndmask_b32_e32 v77, v164, v77, vcc
	ds_write_b32 v163, v77
	ds_read_b128 v[80:83], v69
	ds_read_b128 v[84:87], v73
	ds_read_b128 v[148:151], v96
	ds_read_b128 v[152:155], v96 offset:64
	ds_read_b128 v[88:91], v70
	ds_read_b128 v[200:203], v74
	ds_read_b128 v[166:169], v96 offset:2304
	ds_read_b128 v[170:173], v96 offset:2368
	ds_read_b128 v[98:101], v71
	ds_read_b128 v[102:105], v75
	ds_read_b128 v[106:109], v72
	ds_read_b128 v[110:113], v76
	s_cmp_eq_u32 s1, 0
	s_cbranch_scc1 .Lmy_a_nonuni
	s_setprio 1
	s_waitcnt lgkmcnt(9)
	v_mfma_f32_16x16x32_bf16 v[80:83], v[148:151], v[26:29], v[80:83]
	v_mfma_f32_16x16x32_bf16 v[84:87], v[148:151], v[34:37], v[84:87]
	ds_read_b128 v[174:177], v96 offset:4608
	ds_read_b128 v[178:181], v96 offset:4672
	ds_read_b128 v[182:185], v96 offset:6912
	ds_read_b128 v[186:189], v96 offset:6976
	s_waitcnt lgkmcnt(12)
	v_mfma_f32_16x16x32_bf16 v[80:83], v[152:155], v[30:33], v[80:83]
	v_mfma_f32_16x16x32_bf16 v[84:87], v[152:155], v[38:41], v[84:87]
	s_waitcnt lgkmcnt(9)
	v_mfma_f32_16x16x32_bf16 v[88:91], v[166:169], v[26:29], v[88:91]
	v_mfma_f32_16x16x32_bf16 v[200:203], v[166:169], v[34:37], v[200:203]
	s_waitcnt lgkmcnt(8)
	v_mfma_f32_16x16x32_bf16 v[88:91], v[170:173], v[30:33], v[88:91]
	v_mfma_f32_16x16x32_bf16 v[200:203], v[170:173], v[38:41], v[200:203]
	s_waitcnt lgkmcnt(3)
	v_mfma_f32_16x16x32_bf16 v[98:101], v[174:177], v[26:29], v[98:101]
	v_mfma_f32_16x16x32_bf16 v[102:105], v[174:177], v[34:37], v[102:105]
	s_waitcnt lgkmcnt(2)
	v_mfma_f32_16x16x32_bf16 v[98:101], v[178:181], v[30:33], v[98:101]
	v_mfma_f32_16x16x32_bf16 v[102:105], v[178:181], v[38:41], v[102:105]
	s_waitcnt lgkmcnt(1)
	v_mfma_f32_16x16x32_bf16 v[106:109], v[182:185], v[26:29], v[106:109]
	v_mfma_f32_16x16x32_bf16 v[110:113], v[182:185], v[34:37], v[110:113]
	s_waitcnt lgkmcnt(0)
	v_mfma_f32_16x16x32_bf16 v[106:109], v[186:189], v[30:33], v[106:109]
	v_mfma_f32_16x16x32_bf16 v[110:113], v[186:189], v[38:41], v[110:113]
	s_setprio 0
	s_add_i32 s0, s14, 1
	v_mov_b32_e32 v161, s0
	s_add_i32 s0, s15, 0xffffff00
	v_mov_b32_e32 v165, s0
	ds_read_u8 v97, v161
	ds_read_b32 v217, v165
	ds_read_b128 v[148:151], v96 offset:14336
	ds_read_b128 v[152:155], v96 offset:16640
	ds_read_b128 v[166:169], v96 offset:18944
	ds_read_b128 v[170:173], v96 offset:21248
	ds_read_b128 v[174:177], v96 offset:14400
	ds_read_b128 v[178:181], v96 offset:16704
	ds_read_b128 v[182:185], v96 offset:19008
	ds_read_b128 v[186:189], v96 offset:21312

; #define LAS __attribute__((address_space(3)))
; __device__ __forceinline__ float fexp2(float x) { return __builtin_amdgcn_exp2f(x); }
; template <int DQK, int VAR> ...
;     ...
;         __builtin_amdgcn_sched_barrier(0);
;         __builtin_amdgcn_s_setprio(1);
; #pragma unroll
;         for (int c = 0; c < 2; ++c) {
;             s[0][ch * 2 + c] = (f32x4){sinit, sinit, sinit, sinit}; s[1][ch * 2 + c] = s[0][ch * 2 + c];
; #pragma unroll
;             for (int ks = 0; ks < DQK / 32; ++ks) {
;                 s[0][ch * 2 + c] = __builtin_amdgcn_mfma_f32_16x16x32_bf16(kfr[c][ks], qf[0][ks], s[0][ch * 2 + c], 0, 0, 0);
;                 s[1][ch * 2 + c] = __builtin_amdgcn_mfma_f32_16x16x32_bf16(kfr[c][ks], qf[1][ks], s[1][ch * 2 + c], 0, 0, 0);
;             }
;         }
;         __builtin_amdgcn_s_setprio(0);
;         __builtin_amdgcn_sched_barrier(0);
;     }
;     __builtin_amdgcn_s_setprio(0);
;     __builtin_amdgcn_sched_barrier(0);
; #pragma unroll
;     for (int kk = 0; kk < 2; ++kk)
; #pragma unroll
;         for (int dt = 0; dt < 4; ++dt) {
;             const LAS bf16_t* vp = sVt + (dt * 16 + lr) * VP + kk * 32 + lg * 4;
;             const u32x2 v0 = *(const LAS u32x2*)vp, v1 = *(const LAS u32x2*)(vp + 16);
;             vfr[kk][dt].x = v0.x; vfr[kk][dt].y = v0.y; vfr[kk][dt].z = v1.x; vfr[kk][dt].w = v1.y;
;         }
;     __builtin_amdgcn_sched_barrier(0);
; #pragma unroll
;     for (int qt = 0; qt < 2; ++qt) {
;         const int dq = qi + qt * 16 - key0 - lg * 4;
;         const LAS float* bp = sBias + (dq + 33);
;         float ps = 0.f;
; #pragma unroll
;         for (int c = 0; c < 4; ++c)
; #pragma unroll
;             for (int j = 0; j < 4; ++j) {
;                 float val = s[qt][c][j]; float pv;
;                 if (VAR == 0) pv = fexp2(val);
;                 else if (VAR == 1) { pv = fexp2(val); pv = (dq >= c * 16 + j) ? pv : 0.f; }
;                 else if (VAR == 2) { pv = fexp2(val + bp[63 - (c * 16 + j)]); }
;                 else if (VAR == 3) { pv = fexp2(val); pv = __uint_as_float(__float_as_uint(pv) & (unsigned)__builtin_amdgcn_sbfe((int)(c < 2 ? mlo[qt] : mhi[qt]), (c & 1) * 16 + j, 1)); }
;                 else { pv = fexp2(val + bp[63 - (c * 16 + j)]); pv = __uint_as_float(__float_as_uint(pv) & (unsigned)__builtin_amdgcn_sbfe((int)(c < 2 ? mlo[qt] : mhi[qt]), (c & 1) * 16 + j, 1)); }
.Lmy_a_nonuni:
	v_add_u32_e32 v165, 0x13cb4, v123
	s_setprio 1
	s_waitcnt lgkmcnt(9)
	v_mfma_f32_16x16x32_bf16 v[80:83], v[148:151], v[26:29], v[80:83]
	v_mfma_f32_16x16x32_bf16 v[84:87], v[148:151], v[34:37], v[84:87]
	ds_read_b128 v[174:177], v96 offset:4608
	ds_read_b128 v[178:181], v96 offset:4672
	ds_read_b128 v[182:185], v96 offset:6912
	ds_read_b128 v[186:189], v96 offset:6976
	s_waitcnt lgkmcnt(12)
	v_mfma_f32_16x16x32_bf16 v[80:83], v[152:155], v[30:33], v[80:83]
	v_mfma_f32_16x16x32_bf16 v[84:87], v[152:155], v[38:41], v[84:87]
	s_waitcnt lgkmcnt(9)
	v_mfma_f32_16x16x32_bf16 v[88:91], v[166:169], v[26:29], v[88:91]
	v_mfma_f32_16x16x32_bf16 v[200:203], v[166:169], v[34:37], v[200:203]
	s_waitcnt lgkmcnt(8)
	v_mfma_f32_16x16x32_bf16 v[88:91], v[170:173], v[30:33], v[88:91]
	v_mfma_f32_16x16x32_bf16 v[200:203], v[170:173], v[38:41], v[200:203]
	ds_read2_b32 v[78:79], v165 offset0:66 offset1:67
	ds_read2_b32 v[190:191], v165 offset0:64 offset1:65
	ds_read2_b32 v[136:137], v165 offset0:50 offset1:51
	ds_read2_b32 v[214:215], v165 offset0:48 offset1:49
	ds_read2_b32 v[238:239], v165 offset0:34 offset1:35
	ds_read2_b32 v[92:93], v165 offset0:32 offset1:33
	s_waitcnt lgkmcnt(9)
	v_mfma_f32_16x16x32_bf16 v[98:101], v[174:177], v[26:29], v[98:101]
	v_mfma_f32_16x16x32_bf16 v[102:105], v[174:177], v[34:37], v[102:105]
	s_waitcnt lgkmcnt(8)
	v_mfma_f32_16x16x32_bf16 v[98:101], v[178:181], v[30:33], v[98:101]
	v_mfma_f32_16x16x32_bf16 v[102:105], v[178:181], v[38:41], v[102:105]
	s_waitcnt lgkmcnt(7)
	v_mfma_f32_16x16x32_bf16 v[106:109], v[182:185], v[26:29], v[106:109]
	v_mfma_f32_16x16x32_bf16 v[110:113], v[182:185], v[34:37], v[110:113]
	s_waitcnt lgkmcnt(6)
	v_mfma_f32_16x16x32_bf16 v[106:109], v[186:189], v[30:33], v[106:109]
	v_mfma_f32_16x16x32_bf16 v[110:113], v[186:189], v[38:41], v[110:113]
	s_setprio 0
	ds_read2_b32 v[218:219], v165 offset0:18 offset1:19
	ds_read2_b32 v[220:221], v165 offset0:16 offset1:17
	ds_read2_b32 v[222:223], v165 offset0:2 offset1:3
	ds_read2_b32 v[224:225], v165 offset1:1
	s_add_i32 s0, s14, 1
	v_mov_b32_e32 v161, s0
	s_add_i32 s0, s15, 0xffffff00
	v_mov_b32_e32 v66, s0
	ds_read_u8 v97, v161
	ds_read_b32 v217, v66
	ds_read_b128 v[148:151], v96 offset:14336
	ds_read_b128 v[152:155], v96 offset:16640
	s_waitcnt lgkmcnt(12)
	v_pk_add_f32 v[84:85], v[84:85], v[78:79] op_sel:[0,1] op_sel_hi:[1,0]
	v_pk_add_f32 v[86:87], v[86:87], v[190:191] op_sel:[0,1] op_sel_hi:[1,0]
	ds_read_b128 v[166:169], v96 offset:18944
	ds_read_b128 v[170:173], v96 offset:21248
	s_waitcnt lgkmcnt(12)
	v_pk_add_f32 v[80:81], v[80:81], v[136:137] op_sel:[0,1] op_sel_hi:[1,0]
	v_pk_add_f32 v[82:83], v[82:83], v[214:215] op_sel:[0,1] op_sel_hi:[1,0]
	v_pk_add_f32 v[200:201], v[200:201], v[136:137] op_sel:[0,1] op_sel_hi:[1,0]
	v_pk_add_f32 v[202:203], v[202:203], v[214:215] op_sel:[0,1] op_sel_hi:[1,0]
	ds_read_b128 v[174:177], v96 offset:14400
	ds_read_b128 v[178:181], v96 offset:16704
	s_waitcnt lgkmcnt(12)
	v_pk_add_f32 v[88:89], v[88:89], v[238:239] op_sel:[0,1] op_sel_hi:[1,0]
	v_pk_add_f32 v[90:91], v[90:91], v[92:93] op_sel:[0,1] op_sel_hi:[1,0]
	v_pk_add_f32 v[102:103], v[102:103], v[238:239] op_sel:[0,1] op_sel_hi:[1,0]
	v_pk_add_f32 v[104:105], v[104:105], v[92:93] op_sel:[0,1] op_sel_hi:[1,0]
	ds_read_b128 v[182:185], v96 offset:19008
	ds_read_b128 v[186:189], v96 offset:21312
	s_waitcnt lgkmcnt(12)
	v_pk_add_f32 v[98:99], v[98:99], v[218:219] op_sel:[0,1] op_sel_hi:[1,0]
	v_pk_add_f32 v[100:101], v[100:101], v[220:221] op_sel:[0,1] op_sel_hi:[1,0]
	v_pk_add_f32 v[110:111], v[110:111], v[218:219] op_sel:[0,1] op_sel_hi:[1,0]
	v_pk_add_f32 v[112:113], v[112:113], v[220:221] op_sel:[0,1] op_sel_hi:[1,0]
	s_waitcnt lgkmcnt(10)
	v_pk_add_f32 v[106:107], v[106:107], v[222:223] op_sel:[0,1] op_sel_hi:[1,0]
	v_pk_add_f32 v[108:109], v[108:109], v[224:225] op_sel:[0,1] op_sel_hi:[1,0]
	s_branch .Lmy_a_exp
